# v045 + attention Q-prep: row-axis rope table loads issued with the first load batch (one exposed round trip less per unit)
# baseline (speedup 1.0000x reference)
.LBB0_237:
	v_mov_b64_e32 v[30:31], v[14:15]
	v_mov_b64_e32 v[28:29], v[12:13]
	v_mov_b64_e32 v[26:27], v[10:11]
	v_mov_b64_e32 v[24:25], v[8:9]
	v_mov_b64_e32 v[22:23], v[6:7]
	v_mov_b64_e32 v[20:21], v[4:5]
	v_mov_b64_e32 v[18:19], v[2:3]
	v_mov_b64_e32 v[16:17], v[0:1]
	global_load_dwordx2 v[64:65], v[184:185], off
	global_load_dwordx4 v[68:71], v[182:183], off offset:448
	global_load_dwordx4 v[72:75], v[182:183], off offset:464
	global_load_dwordx4 v[20:23], v[182:183], off offset:320
	global_load_dwordx4 v[16:19], v[182:183], off offset:336
	s_lshl_b32 s0, s95, 8
	s_and_b32 s96, s0, 0x3f00
	s_mul_i32 s0, s96, 0x2400
	s_add_u32 s4, s57, s0
	s_addc_u32 s5, s59, 0
	s_lshl_b32 s0, s95, 1
	s_and_b32 s66, s0, 0xffffff80
	s_ashr_i32 s67, s66, 31
	s_lshl_b64 s[0:1], s[66:67], 1
	s_add_u32 s0, s4, s0
	s_addc_u32 s1, s5, s1
	s_ashr_i32 s4, s95, 1
	s_and_b32 s4, s4, 0xffffff80
	s_ashr_i32 s5, s4, 31
	s_lshl_b64 s[68:69], s[4:5], 1
	s_add_u32 s72, s75, s68
	s_addc_u32 s73, s76, s69
	s_add_u32 s70, s77, s68
	v_readfirstlane_b32 s97, v177
	s_addc_u32 s71, s78, s69
	s_lshr_b32 s33, s97, 6
	s_lshl_b32 s8, s33, 5
	v_or_b32_e32 v26, s8, v178
	v_mov_b64_e32 v[24:25], s[0:1]
	s_movk_i32 s0, 0x2400
	v_mad_u64_u32 v[24:25], s[0:1], v26, s0, v[24:25]
	v_lshl_add_u64 v[66:67], v[24:25], 0, v[188:189]
	v_cmp_lt_i32_e64 s[0:1], v212, v211
	global_load_dwordx4 v[94:97], v[66:67], off offset:224
	global_load_dwordx4 v[98:101], v[66:67], off offset:160
	v_cndmask_b32_e64 v52, v210, v212, s[0:1]
	v_cmp_lt_i32_e64 s[0:1], v213, v211
	global_load_dwordx4 v[44:47], v[182:183], off
	global_load_dwordx4 v[40:43], v[182:183], off offset:16
	global_load_dwordx4 v[36:39], v[182:183], off offset:64
	global_load_dwordx4 v[32:35], v[182:183], off offset:80
	global_load_dwordx4 v[104:107], v[182:183], off offset:384
	global_load_dwordx4 v[122:125], v[182:183], off offset:400
	global_load_dwordx4 v[126:129], v[66:67], off offset:192
	global_load_dwordx4 v[136:139], v[66:67], off offset:128
	global_load_dwordx4 v[28:31], v[182:183], off offset:256
	global_load_dwordx4 v[24:27], v[182:183], off offset:272
	global_load_dwordx4 v[48:51], v[182:183], off offset:128
	global_load_dwordx4 v[60:63], v[182:183], off offset:144
	global_load_dwordx4 v[140:143], v[182:183], off offset:192
	global_load_dwordx4 v[144:147], v[182:183], off offset:208
	v_cndmask_b32_e64 v53, v210, v213, s[0:1]
	v_cmp_lt_i32_e64 s[0:1], v214, v211
	v_lshlrev_b32_e32 v76, 2, v52
	v_lshlrev_b32_e32 v77, 2, v53
	v_cndmask_b32_e64 v54, v210, v214, s[0:1]
	v_cmp_lt_i32_e64 s[0:1], v215, v211
	v_lshlrev_b32_e32 v78, 2, v54
	v_or_b32_e32 v134, s96, v178
	v_cndmask_b32_e64 v55, v210, v215, s[0:1]
	v_cmp_lt_i32_e64 s[0:1], v216, v211
	v_lshlrev_b32_e32 v90, 2, v55
	s_mov_b32 s4, 0x7fffffc0
	v_cndmask_b32_e64 v56, v210, v216, s[0:1]
	v_cmp_lt_i32_e64 s[0:1], v217, v211
	v_lshlrev_b32_e32 v102, 2, v56
	v_mov_b32_e32 v195, v181
	v_cndmask_b32_e64 v57, v210, v217, s[0:1]
	v_lshlrev_b32_e32 v108, 2, v57
	global_load_dwordx4 v[52:55], v[66:67], off
	global_load_dwordx4 v[148:151], v[66:67], off offset:32
	global_load_dwordx4 v[56:59], v[66:67], off offset:64
	global_load_dwordx4 v[152:155], v[66:67], off offset:96
	v_add_u32_e32 v202, s8, v134
	v_and_or_b32 v202, v202, s4, v200
	v_lshlrev_b32_e32 v202, 2, v202
	global_load_dwordx4 v[220:223], v202, s[6:7]
	global_load_dwordx4 v[224:227], v202, s[6:7] offset:16
	global_load_dwordx4 v[228:231], v202, s[6:7] offset:32
	global_load_dwordx4 v[232:235], v202, s[6:7] offset:48
	global_load_dwordx4 v[236:239], v202, s[6:7] offset:128
	global_load_dwordx4 v[240:243], v202, s[6:7] offset:144
	global_load_dwordx4 v[244:247], v202, s[6:7] offset:176
	global_load_dwordx4 v[252:255], v202, s[6:7] offset:160
	s_mov_b32 s0, 0x800000
	v_mov_b32_e32 v218, v181
	s_waitcnt vmcnt(32)
	v_max_f32_e64 v66, |v65|, |v65|
	v_max_f32_e64 v67, |v64|, |v64|
	s_waitcnt vmcnt(30)
	v_mov_b32_e32 v64, v74
	v_max_f32_e32 v74, v67, v66
	s_waitcnt vmcnt(28)
	v_mov_b32_e32 v65, v18
	v_mov_b32_e32 v18, v75
	ds_bpermute_b32 v75, v76, v74
	v_mov_b32_e32 v82, v70
	v_mov_b32_e32 v66, v72
	v_mov_b32_e32 v89, v20
	v_mov_b32_e32 v88, v68
	s_waitcnt lgkmcnt(0)
	v_max_f32_e32 v70, v75, v75
	v_max_f32_e32 v70, v74, v70
	ds_bpermute_b32 v72, v77, v70
	v_mov_b32_e32 v67, v16
	v_mov_b32_e32 v16, v73
	v_mov_b32_e32 v83, v22
	v_mov_b32_e32 v22, v71
	s_waitcnt lgkmcnt(0)
	v_max_f32_e32 v20, v72, v72
	v_max_f32_e32 v20, v70, v20
	ds_bpermute_b32 v68, v78, v20
	s_waitcnt vmcnt(25)
	v_mov_b32_e32 v169, v46
	s_waitcnt lgkmcnt(0)
	v_max_f32_e32 v68, v68, v68
	v_max_f32_e32 v20, v20, v68
	ds_bpermute_b32 v68, v90, v20
	s_waitcnt vmcnt(24)
	v_mov_b32_e32 v167, v40
	s_waitcnt vmcnt(23)
	v_mov_b32_e32 v163, v36
	s_waitcnt vmcnt(19)
	v_and_b32_e32 v114, 0xffff0000, v129
	v_and_b32_e32 v118, 0xffff0000, v128
	s_waitcnt lgkmcnt(0)
	v_max_f32_e32 v68, v68, v68
	v_max_f32_e32 v20, v20, v68
	ds_bpermute_b32 v68, v102, v20
	v_and_b32_e32 v78, 0xffff0000, v97
	v_and_b32_e32 v84, 0xffff0000, v96
	v_lshlrev_b32_e32 v80, 16, v97
	v_lshlrev_b32_e32 v86, 16, v96
	s_waitcnt lgkmcnt(0)
	v_max_f32_e32 v68, v68, v68
	v_max_f32_e32 v20, v20, v68
	ds_bpermute_b32 v68, v108, v20
	v_mov_b32_e32 v72, v78
	v_mov_b32_e32 v73, v84
	v_and_b32_e32 v90, 0xffff0000, v95
	v_mov_b32_e32 v70, v80
	v_mov_b32_e32 v71, v86
	v_pk_mul_f32 v[72:73], v[72:73], v[72:73]
	v_and_b32_e32 v108, 0xffff0000, v94
	v_lshlrev_b32_e32 v92, 16, v95
	v_lshlrev_b32_e32 v102, 16, v94
	v_pk_fma_f32 v[96:97], v[70:71], v[70:71], v[72:73]
	v_mov_b32_e32 v72, v90
	v_mov_b32_e32 v73, v108
	s_waitcnt lgkmcnt(0)
	v_max_f32_e32 v68, v68, v68
	v_mov_b32_e32 v70, v92
	v_mov_b32_e32 v71, v102
	v_pk_mul_f32 v[72:73], v[72:73], v[72:73]
	v_max_f32_e32 v135, v20, v68
	v_pk_fma_f32 v[94:95], v[70:71], v[70:71], v[72:73]
	v_lshlrev_b32_e32 v112, 16, v129
	v_lshlrev_b32_e32 v68, 16, v128
	v_mov_b32_e32 v72, v114
	v_mov_b32_e32 v73, v118
	v_mov_b32_e32 v70, v112
	v_mov_b32_e32 v71, v68
	v_pk_mul_f32 v[72:73], v[72:73], v[72:73]
	s_waitcnt vmcnt(18)
	v_and_b32_e32 v131, 0xffff0000, v137
	v_and_b32_e32 v130, 0xffff0000, v127
	s_waitcnt vmcnt(14)
	v_mov_b32_e32 v40, v61
	s_waitcnt vmcnt(11)
	v_lshlrev_b32_e32 v61, 16, v53
	v_and_b32_e32 v171, 0xffff0000, v53
	s_waitcnt vmcnt(9)
	v_and_b32_e32 v170, 0xffff0000, v57
	v_lshlrev_b32_e32 v173, 16, v52
	v_and_b32_e32 v53, 0xffff0000, v52
	v_and_b32_e32 v52, 0xffff0000, v56
	v_lshlrev_b32_e32 v93, 16, v99
	v_and_b32_e32 v91, 0xffff0000, v99
	v_lshlrev_b32_e32 v103, 16, v98
	v_and_b32_e32 v109, 0xffff0000, v98
	v_pk_fma_f32 v[98:99], v[70:71], v[70:71], v[72:73]
	v_lshlrev_b32_e32 v71, 16, v137
	v_lshlrev_b32_e32 v70, 16, v127
	v_pk_mul_f32 v[74:75], v[130:131], v[130:131]
	v_mov_b32_e32 v158, v144
	s_waitcnt vmcnt(8)
	v_lshlrev_b32_e32 v144, 16, v153
	v_and_b32_e32 v160, 0xffff0000, v153
	v_mov_b32_e32 v36, v141
	v_lshlrev_b32_e32 v141, 16, v55
	v_mov_b32_e32 v153, v42
	v_and_b32_e32 v165, 0xffff0000, v55
	v_mov_b32_e32 v42, v63
	v_lshlrev_b32_e32 v63, 16, v54
	v_mov_b32_e32 v166, v60
	v_and_b32_e32 v55, 0xffff0000, v54
	v_and_b32_e32 v54, 0xffff0000, v58
	v_lshlrev_b32_e32 v60, 16, v57
	v_pk_mul_f32 v[128:129], v[170:171], v[170:171]
	v_lshlrev_b32_e32 v172, 16, v56
	v_pk_mul_f32 v[56:57], v[52:53], v[52:53]
	v_lshlrev_b32_e32 v81, 16, v101
	v_and_b32_e32 v79, 0xffff0000, v101
	v_lshlrev_b32_e32 v87, 16, v100
	v_and_b32_e32 v85, 0xffff0000, v100
	v_mov_b32_e32 v20, v69
	v_lshlrev_b32_e32 v113, 16, v139
	v_and_b32_e32 v115, 0xffff0000, v139
	v_lshlrev_b32_e32 v69, 16, v138
	v_and_b32_e32 v119, 0xffff0000, v138
	v_pk_fma_f32 v[100:101], v[70:71], v[70:71], v[74:75]
	v_lshlrev_b32_e32 v75, 16, v136
	v_and_b32_e32 v133, 0xffff0000, v136
	v_lshlrev_b32_e32 v137, 16, v151
	v_lshlrev_b32_e32 v136, 16, v155
	v_mov_b32_e32 v138, v146
	v_mov_b32_e32 v139, v34
	v_and_b32_e32 v157, 0xffff0000, v151
	v_and_b32_e32 v156, 0xffff0000, v155
	v_mov_b32_e32 v34, v147
	v_lshlrev_b32_e32 v147, 16, v150
	v_lshlrev_b32_e32 v146, 16, v154
	v_mov_b32_e32 v159, v32
	v_and_b32_e32 v151, 0xffff0000, v150
	v_and_b32_e32 v150, 0xffff0000, v154
	v_mov_b32_e32 v32, v145
	v_lshlrev_b32_e32 v145, 16, v149
	v_mov_b32_e32 v154, v142
	v_mov_b32_e32 v155, v38
	v_and_b32_e32 v161, 0xffff0000, v149
	v_mov_b32_e32 v38, v143
	v_lshlrev_b32_e32 v143, 16, v148
	v_lshlrev_b32_e32 v142, 16, v152
	v_mov_b32_e32 v162, v140
	v_and_b32_e32 v149, 0xffff0000, v148
	v_and_b32_e32 v148, 0xffff0000, v152
	v_lshlrev_b32_e32 v140, 16, v59
	v_mov_b32_e32 v152, v62
	v_and_b32_e32 v164, 0xffff0000, v59
	v_lshlrev_b32_e32 v62, 16, v58
	v_pk_mul_f32 v[58:59], v[54:55], v[54:55]
	v_pk_fma_f32 v[128:129], v[60:61], v[60:61], v[128:129]
	v_pk_fma_f32 v[56:57], v[172:173], v[172:173], v[56:57]
	v_lshlrev_b32_e32 v74, 16, v126
	v_and_b32_e32 v132, 0xffff0000, v126
	v_pk_mul_f32 v[126:127], v[164:165], v[164:165]
	v_pk_fma_f32 v[58:59], v[62:63], v[62:63], v[58:59]
	v_add_f32_e32 v46, v57, v129
	v_mov_b32_e32 v116, v124
	v_mov_b32_e32 v117, v26
	v_mov_b32_e32 v26, v125
	v_pk_mul_f32 v[124:125], v[148:149], v[148:149]
	v_pk_fma_f32 v[126:127], v[140:141], v[140:141], v[126:127]
	v_add_f32_e32 v46, v59, v46
	v_mov_b32_e32 v120, v122
	v_mov_b32_e32 v121, v24
	v_mov_b32_e32 v24, v123
	v_pk_mul_f32 v[122:123], v[160:161], v[160:161]
	v_pk_fma_f32 v[124:125], v[142:143], v[142:143], v[124:125]
	v_add_f32_e32 v46, v127, v46
	v_pk_mul_f32 v[110:111], v[150:151], v[150:151]
	v_pk_fma_f32 v[122:123], v[144:145], v[144:145], v[122:123]
	v_add_f32_e32 v46, v125, v46
	v_mov_b32_e32 v76, v104
	v_mov_b32_e32 v77, v28
	v_mov_b32_e32 v28, v105
	v_pk_mul_f32 v[104:105], v[156:157], v[156:157]
	v_pk_fma_f32 v[110:111], v[146:147], v[146:147], v[110:111]
	v_add_f32_e32 v46, v123, v46
	v_pk_fma_f32 v[104:105], v[136:137], v[136:137], v[104:105]
	v_add_f32_e32 v46, v111, v46
	v_add_f32_e32 v46, v105, v46
	v_pk_add_f32 v[56:57], v[56:57], v[46:47] op_sel_hi:[1,0]
	v_mov_b32_e32 v72, v106
	v_pk_add_f32 v[56:57], v[128:129], v[56:57]
	v_mov_b32_e32 v73, v30
	v_pk_add_f32 v[56:57], v[58:59], v[56:57]
	v_mov_b32_e32 v30, v107
	v_pk_add_f32 v[56:57], v[126:127], v[56:57]
	v_pk_mul_f32 v[106:107], v[132:133], v[132:133]
	v_pk_add_f32 v[56:57], v[124:125], v[56:57]
	v_pk_fma_f32 v[106:107], v[74:75], v[74:75], v[106:107]
	v_pk_add_f32 v[56:57], v[122:123], v[56:57]
	v_mul_f32_e32 v46, v69, v69
	v_pk_add_f32 v[56:57], v[110:111], v[56:57]
	v_fmac_f32_e32 v46, v119, v119
	v_pk_add_f32 v[56:57], v[104:105], v[56:57]
	v_mov_b32_e32 v168, v50
	v_pk_add_f32 v[56:57], v[106:107], v[56:57] op_sel:[1,0] op_sel_hi:[0,1]
	v_pk_add_f32 v[56:57], v[100:101], v[56:57] op_sel:[1,0] op_sel_hi:[0,1]
	v_pk_add_f32 v[56:57], v[46:47], v[56:57] op_sel_hi:[0,1]
	v_mul_f32_e32 v46, v113, v113
	v_fmac_f32_e32 v46, v115, v115
	v_pk_add_f32 v[56:57], v[46:47], v[56:57] op_sel_hi:[0,1]
	v_mul_f32_e32 v46, v103, v103
	v_fmac_f32_e32 v46, v109, v109
	v_pk_add_f32 v[56:57], v[46:47], v[56:57] op_sel_hi:[0,1]
	v_mul_f32_e32 v46, v93, v93
	v_fmac_f32_e32 v46, v91, v91
	v_pk_add_f32 v[56:57], v[46:47], v[56:57] op_sel_hi:[0,1]
	v_mul_f32_e32 v46, v87, v87
	v_fmac_f32_e32 v46, v85, v85
	v_pk_add_f32 v[56:57], v[46:47], v[56:57] op_sel_hi:[0,1]
	v_mul_f32_e32 v46, v81, v81
	v_fmac_f32_e32 v46, v79, v79
	v_pk_add_f32 v[56:57], v[46:47], v[56:57] op_sel_hi:[0,1]
	v_pk_add_f32 v[56:57], v[106:107], v[56:57]
	s_nop 0
	v_pk_add_f32 v[56:57], v[100:101], v[56:57]
	s_nop 0
	v_pk_add_f32 v[56:57], v[98:99], v[56:57] op_sel:[1,0] op_sel_hi:[0,1]
	v_pk_add_f32 v[56:57], v[98:99], v[56:57]
	s_nop 0
	v_pk_add_f32 v[56:57], v[94:95], v[56:57] op_sel:[1,0] op_sel_hi:[0,1]
	v_pk_add_f32 v[56:57], v[94:95], v[56:57]
	s_nop 0
	v_pk_add_f32 v[56:57], v[96:97], v[56:57] op_sel:[1,0] op_sel_hi:[0,1]
	v_pk_add_f32 v[56:57], v[96:97], v[56:57]
	s_nop 0
	v_mov_b32_e32 v46, v56
	s_nop 1
	v_permlane32_swap_b32_e32 v56, v46
	v_add_f32_e32 v46, v56, v46
	v_fmamk_f32 v46, v46, 0x3c000000, v208
	v_mul_f32_e32 v50, 0x4b800000, v46
	v_cmp_gt_f32_e64 s[0:1], s0, v46
	s_nop 1
	v_cndmask_b32_e64 v46, v46, v50, s[0:1]
	v_rsq_f32_e32 v56, v46
	v_mov_b32_e32 v46, v51
	v_mov_b32_e32 v51, v44
	v_mov_b32_e32 v50, v48
	v_mul_f32_e32 v44, 0x45800000, v56
	v_cndmask_b32_e64 v174, v56, v44, s[0:1]
	v_pk_mul_f32 v[40:41], v[174:175], v[40:41] op_sel_hi:[0,1]
	v_pk_mul_f32 v[36:37], v[174:175], v[36:37] op_sel_hi:[0,1]
	v_pk_mul_f32 v[106:107], v[40:41], v[54:55]
	v_pk_mul_f32 v[40:41], v[174:175], v[152:153] op_sel_hi:[0,1]
	v_pk_mul_f32 v[96:97], v[36:37], v[148:149]
	v_pk_mul_f32 v[36:37], v[174:175], v[154:155] op_sel_hi:[0,1]
	v_pk_mul_f32 v[50:51], v[174:175], v[50:51] op_sel_hi:[0,1]
	v_mov_b32_e32 v44, v49
	v_pk_mul_f32 v[104:105], v[40:41], v[140:141]
	v_pk_mul_f32 v[40:41], v[174:175], v[42:43] op_sel_hi:[0,1]
	v_pk_mul_f32 v[94:95], v[36:37], v[144:145]
	v_pk_mul_f32 v[36:37], v[174:175], v[38:39] op_sel_hi:[0,1]
	v_pk_mul_f32 v[32:33], v[174:175], v[32:33] op_sel_hi:[0,1]
	v_pk_mul_f32 v[128:129], v[50:51], v[172:173]
	v_pk_mul_f32 v[44:45], v[174:175], v[44:45] op_sel_hi:[0,1]
	v_pk_mul_f32 v[100:101], v[40:41], v[164:165]
	v_pk_mul_f32 v[40:41], v[174:175], v[162:163] op_sel_hi:[0,1]
	v_pk_mul_f32 v[42:43], v[36:37], v[160:161]
	v_pk_mul_f32 v[36:37], v[174:175], v[158:159] op_sel_hi:[0,1]
	v_pk_mul_f32 v[38:39], v[32:33], v[150:151]
	v_pk_mul_f32 v[32:33], v[174:175], v[138:139] op_sel_hi:[0,1]
	v_pk_mul_f32 v[126:127], v[44:45], v[52:53]
	v_pk_mul_f32 v[44:45], v[174:175], v[168:169] op_sel_hi:[0,1]
	v_pk_mul_f32 v[98:99], v[40:41], v[142:143]
	v_pk_mul_f32 v[40:41], v[36:37], v[146:147]
	v_pk_mul_f32 v[36:37], v[32:33], v[136:137]
	v_pk_mul_f32 v[32:33], v[174:175], v[34:35] op_sel_hi:[0,1]
	v_mul_f32_e32 v34, v129, v129
	v_pk_mul_f32 v[124:125], v[44:45], v[60:61]
	v_pk_mul_f32 v[44:45], v[174:175], v[46:47] op_sel_hi:[0,1]
	v_fmac_f32_e32 v34, v127, v127
	v_pk_mul_f32 v[122:123], v[44:45], v[170:171]
	v_pk_mul_f32 v[44:45], v[174:175], v[166:167] op_sel_hi:[0,1]
	v_fmac_f32_e32 v34, v125, v125
	v_pk_mul_f32 v[110:111], v[44:45], v[62:63]
	v_fmac_f32_e32 v34, v123, v123
	v_fmac_f32_e32 v34, v111, v111
	v_fmac_f32_e32 v34, v107, v107
	v_fmac_f32_e32 v34, v105, v105
	v_fmac_f32_e32 v34, v101, v101
	v_fmac_f32_e32 v34, v99, v99
	v_fmac_f32_e32 v34, v97, v97
	v_fmac_f32_e32 v34, v95, v95
	v_fmac_f32_e32 v34, v43, v43
	v_fmac_f32_e32 v34, v41, v41
	v_fmac_f32_e32 v34, v39, v39
	v_pk_mul_f32 v[32:33], v[32:33], v[156:157]
	v_fmac_f32_e32 v34, v37, v37
	v_fmac_f32_e32 v34, v33, v33
	v_pk_fma_f32 v[34:35], v[128:129], v[128:129], v[34:35] op_sel_hi:[1,1,0]
	v_pk_mul_f32 v[44:45], v[174:175], v[76:77] op_sel_hi:[0,1]
	v_pk_fma_f32 v[34:35], v[126:127], v[126:127], v[34:35]
	v_pk_mul_f32 v[76:77], v[44:45], v[74:75]
	v_pk_fma_f32 v[34:35], v[124:125], v[124:125], v[34:35]
	v_pk_mul_f32 v[28:29], v[174:175], v[28:29] op_sel_hi:[0,1]
	v_pk_fma_f32 v[34:35], v[122:123], v[122:123], v[34:35]
	v_mul_f32_e32 v44, v77, v77
	v_pk_fma_f32 v[34:35], v[110:111], v[110:111], v[34:35]
	v_pk_mul_f32 v[74:75], v[28:29], v[132:133]
	v_pk_fma_f32 v[34:35], v[106:107], v[106:107], v[34:35]
	v_mul_f32_e32 v28, v75, v75
	v_pk_fma_f32 v[34:35], v[104:105], v[104:105], v[34:35]
	v_pk_mul_f32 v[30:31], v[174:175], v[30:31] op_sel_hi:[0,1]
	v_pk_fma_f32 v[34:35], v[100:101], v[100:101], v[34:35]
	v_pk_mul_f32 v[24:25], v[174:175], v[24:25] op_sel_hi:[0,1]
	v_pk_fma_f32 v[34:35], v[98:99], v[98:99], v[34:35]
	v_pk_mul_f32 v[62:63], v[24:25], v[118:119]
	v_pk_fma_f32 v[34:35], v[96:97], v[96:97], v[34:35]
	v_mul_f32_e32 v24, v63, v63
	v_pk_fma_f32 v[34:35], v[94:95], v[94:95], v[34:35]
	v_pk_mul_f32 v[26:27], v[174:175], v[26:27] op_sel_hi:[0,1]
	v_pk_fma_f32 v[34:35], v[42:43], v[42:43], v[34:35]
	v_pk_mul_f32 v[58:59], v[26:27], v[114:115]
	v_pk_fma_f32 v[34:35], v[40:41], v[40:41], v[34:35]
	v_mul_f32_e32 v26, v59, v59
	v_pk_fma_f32 v[34:35], v[38:39], v[38:39], v[34:35]
	v_pk_mul_f32 v[20:21], v[174:175], v[20:21] op_sel_hi:[0,1]
	v_pk_fma_f32 v[34:35], v[36:37], v[36:37], v[34:35]
	v_pk_mul_f32 v[54:55], v[20:21], v[108:109]
	v_pk_fma_f32 v[34:35], v[32:33], v[32:33], v[34:35]
	v_mul_f32_e32 v20, v55, v55
	v_pk_add_f32 v[34:35], v[44:45], v[34:35] op_sel_hi:[0,1]
	v_pk_add_f32 v[28:29], v[28:29], v[34:35] op_sel_hi:[0,1]
	v_pk_mul_f32 v[34:35], v[174:175], v[72:73] op_sel_hi:[0,1]
	v_pk_mul_f32 v[72:73], v[34:35], v[70:71]
	v_pk_mul_f32 v[70:71], v[30:31], v[130:131]
	v_mul_f32_e32 v34, v73, v73
	v_pk_add_f32 v[28:29], v[34:35], v[28:29] op_sel_hi:[0,1]
	v_mul_f32_e32 v30, v71, v71
	v_pk_add_f32 v[28:29], v[30:31], v[28:29] op_sel_hi:[0,1]
	v_pk_mul_f32 v[30:31], v[174:175], v[120:121] op_sel_hi:[0,1]
	v_pk_mul_f32 v[68:69], v[30:31], v[68:69]
	v_pk_mul_f32 v[22:23], v[174:175], v[22:23] op_sel_hi:[0,1]
	v_mul_f32_e32 v30, v69, v69
	v_pk_add_f32 v[28:29], v[30:31], v[28:29] op_sel_hi:[0,1]
	v_pk_add_f32 v[24:25], v[24:25], v[28:29] op_sel_hi:[0,1]
	v_pk_mul_f32 v[28:29], v[174:175], v[116:117] op_sel_hi:[0,1]
	v_pk_mul_f32 v[60:61], v[28:29], v[112:113]
	v_pk_mul_f32 v[50:51], v[22:23], v[90:91]
	v_mul_f32_e32 v28, v61, v61
	v_pk_add_f32 v[24:25], v[28:29], v[24:25] op_sel_hi:[0,1]
	v_pk_add_f32 v[24:25], v[26:27], v[24:25] op_sel_hi:[0,1]
	v_pk_mul_f32 v[26:27], v[174:175], v[88:89] op_sel_hi:[0,1]
	v_pk_mul_f32 v[56:57], v[26:27], v[102:103]
	v_mul_f32_e32 v22, v51, v51
	v_mul_f32_e32 v26, v57, v57
	v_pk_add_f32 v[24:25], v[26:27], v[24:25] op_sel_hi:[0,1]
	v_pk_add_f32 v[20:21], v[20:21], v[24:25] op_sel_hi:[0,1]
	v_pk_mul_f32 v[24:25], v[174:175], v[82:83] op_sel_hi:[0,1]
	v_pk_mul_f32 v[52:53], v[24:25], v[92:93]
	v_pk_mul_f32 v[16:17], v[174:175], v[16:17] op_sel_hi:[0,1]
	v_mul_f32_e32 v24, v53, v53
	v_pk_add_f32 v[20:21], v[24:25], v[20:21] op_sel_hi:[0,1]
	v_pk_add_f32 v[20:21], v[22:23], v[20:21] op_sel_hi:[0,1]
	v_pk_mul_f32 v[22:23], v[174:175], v[66:67] op_sel_hi:[0,1]
	v_pk_mul_f32 v[48:49], v[22:23], v[86:87]
	v_pk_mul_f32 v[46:47], v[16:17], v[84:85]
	v_mul_f32_e32 v22, v49, v49
	v_pk_add_f32 v[20:21], v[22:23], v[20:21] op_sel_hi:[0,1]
	v_mul_f32_e32 v16, v47, v47
	v_pk_add_f32 v[16:17], v[16:17], v[20:21] op_sel_hi:[0,1]
	v_pk_mul_f32 v[20:21], v[174:175], v[64:65] op_sel_hi:[0,1]
	v_pk_mul_f32 v[44:45], v[20:21], v[80:81]
	v_pk_mul_f32 v[18:19], v[174:175], v[18:19] op_sel_hi:[0,1]
	v_mul_f32_e32 v20, v45, v45
	v_pk_mul_f32 v[34:35], v[18:19], v[78:79]
	v_pk_add_f32 v[16:17], v[20:21], v[16:17] op_sel_hi:[0,1]
	v_mul_f32_e32 v18, v35, v35
	v_pk_add_f32 v[16:17], v[18:19], v[16:17] op_sel_hi:[0,1]
	v_pk_fma_f32 v[16:17], v[76:77], v[76:77], v[16:17]
	s_mov_b32 s0, 0xf800000
	v_pk_fma_f32 v[16:17], v[74:75], v[74:75], v[16:17]
	v_add_u32_e32 v108, s8, v134
	v_pk_fma_f32 v[16:17], v[72:73], v[72:73], v[16:17]
	v_and_or_b32 v180, v108, s4, v200
	v_pk_fma_f32 v[16:17], v[70:71], v[70:71], v[16:17]
	v_lshl_add_u64 v[102:103], v[180:181], 2, s[6:7]
	v_pk_fma_f32 v[16:17], v[68:69], v[68:69], v[16:17]
	v_lshlrev_b32_e32 v108, 6, v108
	v_pk_fma_f32 v[16:17], v[62:63], v[62:63], v[16:17]
	s_nop 0
	v_pk_fma_f32 v[16:17], v[60:61], v[60:61], v[16:17]
	s_nop 0
	v_pk_fma_f32 v[16:17], v[58:59], v[58:59], v[16:17]
	s_nop 0
	v_pk_fma_f32 v[16:17], v[56:57], v[56:57], v[16:17]
	s_nop 0
	v_pk_fma_f32 v[16:17], v[54:55], v[54:55], v[16:17]
	s_nop 0
	v_pk_fma_f32 v[16:17], v[52:53], v[52:53], v[16:17]
	s_nop 0
	v_pk_fma_f32 v[16:17], v[50:51], v[50:51], v[16:17]
	s_nop 0
	v_pk_fma_f32 v[16:17], v[48:49], v[48:49], v[16:17]
	s_nop 0
	v_pk_fma_f32 v[16:17], v[46:47], v[46:47], v[16:17]
	s_nop 0
	v_pk_fma_f32 v[16:17], v[44:45], v[44:45], v[16:17]
	s_nop 0
	v_pk_fma_f32 v[16:17], v[34:35], v[34:35], v[16:17]
	s_nop 0
	v_mov_b32_e32 v17, v16
	s_nop 1
	v_permlane32_swap_b32_e32 v16, v17
	v_add_f32_e32 v16, v16, v17
	v_mul_f32_e32 v17, 0x4f800000, v16
	v_cmp_gt_f32_e64 s[0:1], s0, v16
	s_nop 1
	v_cndmask_b32_e64 v16, v16, v17, s[0:1]
	v_sqrt_f32_e32 v17, v16
	s_nop 0
	v_add_u32_e32 v18, -1, v17
	v_fma_f32 v19, -v18, v17, v16
	v_cmp_ge_f32_e64 s[4:5], 0, v19
	v_add_u32_e32 v19, 1, v17
	s_nop 0
	v_cndmask_b32_e64 v18, v17, v18, s[4:5]
	v_fma_f32 v17, -v19, v17, v16
	v_cmp_lt_f32_e64 s[4:5], 0, v17
	s_nop 1
	v_cndmask_b32_e64 v17, v18, v19, s[4:5]
	v_mul_f32_e32 v18, 0x37800000, v17
	v_cndmask_b32_e64 v17, v17, v18, s[0:1]
	v_cmp_class_f32_e64 s[0:1], v16, v209
	s_movk_i32 s4, 0x4000
	s_nop 0
	v_cndmask_b32_e64 v16, v17, v16, s[0:1]
	v_mul_f32_e32 v16, 0x3e0293ee, v16
	v_mul_f32_e32 v16, 0xc13504f3, v16
	v_mul_f32_e32 v16, v16, v135
	v_mul_f32_e32 v16, 0x3f801062, v16
	v_max_f32_e32 v16, 0xc2700000, v16
	v_mov_b32_e32 v17, v16
	v_mov_b32_e32 v18, v16
	v_mov_b32_e32 v19, v16
	v_mov_b32_e32 v20, v16
	v_mov_b32_e32 v21, v16
	v_mov_b32_e32 v22, v16
	v_mov_b32_e32 v23, v16
	v_mov_b32_e32 v24, v16
	v_mov_b32_e32 v25, v16
	v_mov_b32_e32 v26, v16
	v_mov_b32_e32 v27, v16
	v_mov_b32_e32 v28, v16
	v_mov_b32_e32 v29, v16
	v_mov_b32_e32 v30, v16
	v_mov_b32_e32 v31, v16
	s_waitcnt vmcnt(0)
	v_mov_b64_e32 v[64:65], v[220:221]
	v_mov_b64_e32 v[66:67], v[222:223]
	v_mov_b64_e32 v[78:79], v[224:225]
	v_mov_b64_e32 v[80:81], v[226:227]
	v_mov_b64_e32 v[82:83], v[228:229]
	v_mov_b64_e32 v[84:85], v[230:231]
	v_mov_b64_e32 v[86:87], v[232:233]
	v_mov_b64_e32 v[88:89], v[234:235]
	v_mov_b64_e32 v[90:91], v[236:237]
	v_mov_b64_e32 v[92:93], v[238:239]
	v_mov_b64_e32 v[112:113], v[240:241]
	v_mov_b64_e32 v[114:115], v[242:243]
	v_mov_b64_e32 v[116:117], v[244:245]
	v_mov_b64_e32 v[118:119], v[246:247]
	v_mov_b64_e32 v[130:131], v[252:253]
	v_mov_b64_e32 v[132:133], v[254:255]
	s_movk_i32 s0, 0xfc0
	v_and_or_b32 v108, v108, s0, v200
	v_lshlrev_b32_e32 v108, 2, v108
	s_lshr_b32 s0, s97, 3
	s_and_b32 s0, s0, 0x1ffffff0
	s_waitcnt vmcnt(7)
	v_pk_mul_f32 v[102:103], v[128:129], v[64:65] op_sel:[1,0] op_sel_hi:[0,1]
	v_pk_mul_f32 v[64:65], v[128:129], v[64:65]
	v_sub_f32_e32 v102, v102, v103
	v_add_f32_e32 v64, v64, v65
	v_mul_f32_e32 v120, 0x3e0293ee, v64
	v_pk_mul_f32 v[64:65], v[126:127], v[66:67] op_sel:[1,0] op_sel_hi:[0,1]
	v_sub_f32_e32 v64, v64, v65
	v_mul_f32_e32 v121, 0x3e0293ee, v64
	v_pk_mul_f32 v[64:65], v[126:127], v[66:67]
	v_mul_f32_e32 v109, 0x3e0293ee, v102
	v_add_f32_e32 v64, v64, v65
	v_mul_f32_e32 v126, 0x3e0293ee, v64
	s_waitcnt vmcnt(6)
	v_pk_mul_f32 v[64:65], v[124:125], v[78:79] op_sel:[1,0] op_sel_hi:[0,1]
	v_sub_f32_e32 v64, v64, v65
	v_mul_f32_e32 v127, 0x3e0293ee, v64
	v_pk_mul_f32 v[64:65], v[124:125], v[78:79]
	s_nop 0
	v_add_f32_e32 v64, v64, v65
	v_mul_f32_e32 v124, 0x3e0293ee, v64
	v_pk_mul_f32 v[64:65], v[122:123], v[80:81] op_sel:[1,0] op_sel_hi:[0,1]
	v_sub_f32_e32 v64, v64, v65
	v_mul_f32_e32 v125, 0x3e0293ee, v64
	v_pk_mul_f32 v[64:65], v[122:123], v[80:81]
	s_nop 0
	v_add_f32_e32 v102, v64, v65
	global_load_dwordx4 v[64:67], v108, s[6:7] offset:16
	global_load_dwordx4 v[78:81], v108, s[6:7]
	v_mul_f32_e32 v122, 0x3e0293ee, v102
	s_waitcnt vmcnt(7)
	v_pk_mul_f32 v[102:103], v[110:111], v[82:83] op_sel:[1,0] op_sel_hi:[0,1]
	v_pk_mul_f32 v[82:83], v[110:111], v[82:83]
	v_sub_f32_e32 v102, v102, v103
	v_add_f32_e32 v82, v82, v83
	v_mul_f32_e32 v110, 0x3e0293ee, v82
	v_pk_mul_f32 v[82:83], v[106:107], v[84:85] op_sel:[1,0] op_sel_hi:[0,1]
	v_sub_f32_e32 v82, v82, v83
	v_mul_f32_e32 v111, 0x3e0293ee, v82
	v_pk_mul_f32 v[82:83], v[106:107], v[84:85]
	v_mul_f32_e32 v123, 0x3e0293ee, v102
	v_add_f32_e32 v82, v82, v83
	v_mul_f32_e32 v106, 0x3e0293ee, v82
	s_waitcnt vmcnt(6)
	v_pk_mul_f32 v[82:83], v[104:105], v[86:87] op_sel:[1,0] op_sel_hi:[0,1]
	v_sub_f32_e32 v82, v82, v83
	v_mul_f32_e32 v107, 0x3e0293ee, v82
	v_pk_mul_f32 v[82:83], v[104:105], v[86:87]
	v_pk_mul_f32 v[86:87], v[100:101], v[88:89]
	v_add_f32_e32 v82, v82, v83
	v_mul_f32_e32 v128, 0x3e0293ee, v82
	v_pk_mul_f32 v[82:83], v[100:101], v[88:89] op_sel:[1,0] op_sel_hi:[0,1]
	v_sub_f32_e32 v82, v82, v83
	v_mul_f32_e32 v129, 0x3e0293ee, v82
	global_load_dwordx4 v[82:85], v108, s[6:7] offset:48
	global_load_dwordx4 v[102:105], v108, s[6:7] offset:32
	v_add_f32_e32 v86, v86, v87
	v_mul_f32_e32 v100, 0x3e0293ee, v86
	s_waitcnt vmcnt(7)
	v_pk_mul_f32 v[86:87], v[98:99], v[90:91] op_sel:[1,0] op_sel_hi:[0,1]
	v_sub_f32_e32 v86, v86, v87
	v_mul_f32_e32 v101, 0x3e0293ee, v86
	v_pk_mul_f32 v[86:87], v[98:99], v[90:91]
	s_nop 0
	v_add_f32_e32 v86, v86, v87
	v_mul_f32_e32 v98, 0x3e0293ee, v86
	v_pk_mul_f32 v[86:87], v[96:97], v[92:93] op_sel:[1,0] op_sel_hi:[0,1]
	v_sub_f32_e32 v86, v86, v87
	v_mul_f32_e32 v99, 0x3e0293ee, v86
	v_pk_mul_f32 v[86:87], v[96:97], v[92:93]
	s_nop 0
	v_add_f32_e32 v86, v86, v87
	v_mul_f32_e32 v96, 0x3e0293ee, v86
	s_waitcnt vmcnt(6)
	v_pk_mul_f32 v[86:87], v[94:95], v[112:113] op_sel:[1,0] op_sel_hi:[0,1]
	v_sub_f32_e32 v86, v86, v87
	v_mul_f32_e32 v97, 0x3e0293ee, v86
	v_pk_mul_f32 v[86:87], v[94:95], v[112:113]
	v_pk_mul_f32 v[94:95], v[42:43], v[114:115] op_sel:[1,0] op_sel_hi:[0,1]
	v_add_f32_e32 v86, v86, v87
	v_mul_f32_e32 v112, 0x3e0293ee, v86
	global_load_dwordx4 v[86:89], v108, s[6:7] offset:144
	global_load_dwordx4 v[90:93], v108, s[6:7] offset:128
	v_pk_mul_f32 v[42:43], v[42:43], v[114:115]
	v_sub_f32_e32 v94, v94, v95
	v_add_f32_e32 v42, v42, v43
	v_mul_f32_e32 v114, 0x3e0293ee, v42
	s_waitcnt vmcnt(6)
	v_pk_mul_f32 v[42:43], v[40:41], v[130:131] op_sel:[1,0] op_sel_hi:[0,1]
	v_pk_mul_f32 v[40:41], v[40:41], v[130:131]
	v_sub_f32_e32 v42, v42, v43
	v_add_f32_e32 v40, v40, v41
	v_mul_f32_e32 v130, 0x3e0293ee, v40
	v_pk_mul_f32 v[40:41], v[38:39], v[132:133] op_sel:[1,0] op_sel_hi:[0,1]
	v_pk_mul_f32 v[38:39], v[38:39], v[132:133]
	v_sub_f32_e32 v40, v40, v41
	v_add_f32_e32 v38, v38, v39
	v_mul_f32_e32 v132, 0x3e0293ee, v38
	v_pk_mul_f32 v[38:39], v[36:37], v[116:117] op_sel:[1,0] op_sel_hi:[0,1]
	v_sub_f32_e32 v38, v38, v39
	v_pk_mul_f32 v[36:37], v[36:37], v[116:117]
	v_mul_f32_e32 v113, 0x3e0293ee, v94
	v_mul_f32_e32 v115, 0x3e0293ee, v42
	v_mul_f32_e32 v131, 0x3e0293ee, v40
	v_mul_f32_e32 v133, 0x3e0293ee, v38
	v_add_f32_e32 v94, v36, v37
	global_load_dwordx4 v[36:39], v108, s[6:7] offset:176
	global_load_dwordx4 v[40:43], v108, s[6:7] offset:160
	v_mul_f32_e32 v108, 0x3e0293ee, v94
	v_pk_mul_f32 v[94:95], v[32:33], v[118:119] op_sel:[1,0] op_sel_hi:[0,1]
	v_pk_mul_f32 v[32:33], v[32:33], v[118:119]
	v_sub_f32_e32 v94, v94, v95
	v_add_f32_e32 v32, v32, v33
	v_mul_f32_e32 v95, 0x3e0293ee, v32
	v_mul_f32_e32 v94, 0x3e0293ee, v94
	v_cvt_pk_bf16_f32 v172, v109, v121
	s_waitcnt vmcnt(6)
	v_pk_mul_f32 v[32:33], v[76:77], v[78:79] op_sel:[1,0] op_sel_hi:[0,1]
	v_sub_f32_e32 v32, v32, v33
	v_mul_f32_e32 v116, 0x3e0293ee, v32
	v_pk_mul_f32 v[32:33], v[76:77], v[78:79]
	v_cvt_pk_bf16_f32 v173, v127, v125
	v_cvt_pk_bf16_f32 v174, v123, v111
	v_cvt_pk_bf16_f32 v175, v107, v129
	v_cvt_pk_bf16_f32 v168, v101, v99
	v_cvt_pk_bf16_f32 v169, v97, v113
	s_nop 0
	v_add_f32_e32 v32, v32, v33
	v_mul_f32_e32 v76, 0x3e0293ee, v32
	v_pk_mul_f32 v[32:33], v[74:75], v[80:81] op_sel:[1,0] op_sel_hi:[0,1]
	v_sub_f32_e32 v32, v32, v33
	v_mul_f32_e32 v77, 0x3e0293ee, v32
	v_pk_mul_f32 v[32:33], v[74:75], v[80:81]
	v_cvt_pk_bf16_f32 v170, v115, v131
	v_cvt_pk_bf16_f32 v171, v133, v94
	v_cvt_pk_bf16_f32 v164, v120, v126
	v_cvt_pk_bf16_f32 v165, v124, v122
	v_cvt_pk_bf16_f32 v166, v110, v106
	s_nop 0
	v_add_f32_e32 v32, v32, v33
	v_mul_f32_e32 v74, 0x3e0293ee, v32
	v_pk_mul_f32 v[32:33], v[72:73], v[64:65] op_sel:[1,0] op_sel_hi:[0,1]
	v_sub_f32_e32 v32, v32, v33
	v_mul_f32_e32 v75, 0x3e0293ee, v32
	v_pk_mul_f32 v[32:33], v[72:73], v[64:65]
	v_cvt_pk_bf16_f32 v167, v128, v100
	v_cvt_pk_bf16_f32 v160, v98, v96
	v_cvt_pk_bf16_f32 v161, v112, v114
	v_cvt_pk_bf16_f32 v162, v130, v132
	v_cvt_pk_bf16_f32 v163, v108, v95
	s_nop 0
	v_add_f32_e32 v32, v32, v33
	v_mul_f32_e32 v64, 0x3e0293ee, v32
	v_pk_mul_f32 v[32:33], v[70:71], v[66:67] op_sel:[1,0] op_sel_hi:[0,1]
	v_sub_f32_e32 v32, v32, v33
	v_mul_f32_e32 v65, 0x3e0293ee, v32
	v_pk_mul_f32 v[32:33], v[70:71], v[66:67]
	v_cvt_pk_bf16_f32 v156, v116, v77
	v_cvt_pk_bf16_f32 v157, v75, v65
	v_mov_b32_e32 v65, v181
	v_add_f32_e32 v32, v32, v33
	v_mul_f32_e32 v66, 0x3e0293ee, v32
	s_waitcnt vmcnt(4)
	v_pk_mul_f32 v[32:33], v[68:69], v[102:103] op_sel:[1,0] op_sel_hi:[0,1]
	v_sub_f32_e32 v32, v32, v33
	v_mul_f32_e32 v67, 0x3e0293ee, v32
	v_pk_mul_f32 v[32:33], v[68:69], v[102:103]
	v_mov_b32_e32 v70, v181
	v_add_f32_e32 v32, v32, v33
	v_mul_f32_e32 v68, 0x3e0293ee, v32
	v_pk_mul_f32 v[32:33], v[62:63], v[104:105] op_sel:[1,0] op_sel_hi:[0,1]
	v_sub_f32_e32 v32, v32, v33
	v_mul_f32_e32 v69, 0x3e0293ee, v32
	v_pk_mul_f32 v[32:33], v[62:63], v[104:105]
	v_cvt_pk_bf16_f32 v158, v67, v69
	v_mov_b32_e32 v67, v181
	v_add_f32_e32 v32, v32, v33
	v_mul_f32_e32 v62, 0x3e0293ee, v32
	v_pk_mul_f32 v[32:33], v[60:61], v[82:83] op_sel:[1,0] op_sel_hi:[0,1]
	v_sub_f32_e32 v32, v32, v33
	v_mul_f32_e32 v63, 0x3e0293ee, v32
	v_pk_mul_f32 v[32:33], v[60:61], v[82:83]
	v_mov_b32_e32 v69, v181
	v_add_f32_e32 v32, v32, v33
	v_mul_f32_e32 v60, 0x3e0293ee, v32
	v_pk_mul_f32 v[32:33], v[58:59], v[84:85] op_sel:[1,0] op_sel_hi:[0,1]
	v_sub_f32_e32 v32, v32, v33
	v_mul_f32_e32 v61, 0x3e0293ee, v32
	v_pk_mul_f32 v[32:33], v[58:59], v[84:85]
	v_cvt_pk_bf16_f32 v159, v63, v61
	v_mov_b32_e32 v61, v181
	v_add_f32_e32 v32, v32, v33
	v_mul_f32_e32 v58, 0x3e0293ee, v32
	s_waitcnt vmcnt(2)
	v_pk_mul_f32 v[32:33], v[56:57], v[90:91] op_sel:[1,0] op_sel_hi:[0,1]
	v_sub_f32_e32 v32, v32, v33
	v_mul_f32_e32 v59, 0x3e0293ee, v32
	v_pk_mul_f32 v[32:33], v[56:57], v[90:91]
	v_mov_b32_e32 v63, v181
	v_add_f32_e32 v32, v32, v33
	v_mul_f32_e32 v56, 0x3e0293ee, v32
	v_pk_mul_f32 v[32:33], v[54:55], v[92:93] op_sel:[1,0] op_sel_hi:[0,1]
	v_sub_f32_e32 v32, v32, v33
	v_mul_f32_e32 v57, 0x3e0293ee, v32
	v_pk_mul_f32 v[32:33], v[54:55], v[92:93]
	v_cvt_pk_bf16_f32 v152, v59, v57
	v_mov_b32_e32 v57, v181
	v_add_f32_e32 v32, v32, v33
	v_mul_f32_e32 v54, 0x3e0293ee, v32
	v_pk_mul_f32 v[32:33], v[52:53], v[86:87] op_sel:[1,0] op_sel_hi:[0,1]
	v_sub_f32_e32 v32, v32, v33
	v_mul_f32_e32 v55, 0x3e0293ee, v32
	v_pk_mul_f32 v[32:33], v[52:53], v[86:87]
	v_mov_b32_e32 v59, v181
	v_add_f32_e32 v32, v32, v33
	v_mul_f32_e32 v52, 0x3e0293ee, v32
	v_pk_mul_f32 v[32:33], v[50:51], v[88:89] op_sel:[1,0] op_sel_hi:[0,1]
	v_sub_f32_e32 v32, v32, v33
	v_mul_f32_e32 v53, 0x3e0293ee, v32
	v_pk_mul_f32 v[32:33], v[50:51], v[88:89]
	v_cvt_pk_bf16_f32 v153, v55, v53
	v_mov_b32_e32 v71, v181
	v_add_f32_e32 v32, v32, v33
	v_mul_f32_e32 v50, 0x3e0293ee, v32
	s_waitcnt vmcnt(0)
	v_pk_mul_f32 v[32:33], v[48:49], v[40:41] op_sel:[1,0] op_sel_hi:[0,1]
	v_sub_f32_e32 v32, v32, v33
	v_mul_f32_e32 v51, 0x3e0293ee, v32
	v_pk_mul_f32 v[32:33], v[48:49], v[40:41]
	v_mov_b32_e32 v72, v181
	v_add_f32_e32 v32, v32, v33
	v_mul_f32_e32 v40, 0x3e0293ee, v32
	v_pk_mul_f32 v[32:33], v[46:47], v[42:43] op_sel:[1,0] op_sel_hi:[0,1]
	v_sub_f32_e32 v32, v32, v33
	v_mul_f32_e32 v41, 0x3e0293ee, v32
	v_pk_mul_f32 v[32:33], v[46:47], v[42:43]
	v_cvt_pk_bf16_f32 v154, v51, v41
	v_mov_b32_e32 v73, v181
	v_add_f32_e32 v32, v32, v33
	v_mul_f32_e32 v42, 0x3e0293ee, v32
	v_pk_mul_f32 v[32:33], v[44:45], v[36:37] op_sel:[1,0] op_sel_hi:[0,1]
	v_sub_f32_e32 v32, v32, v33
	v_mul_f32_e32 v43, 0x3e0293ee, v32
	v_pk_mul_f32 v[32:33], v[44:45], v[36:37]
	v_mov_b32_e32 v75, v181
	v_add_f32_e32 v32, v32, v33
	v_mul_f32_e32 v36, 0x3e0293ee, v32
	v_pk_mul_f32 v[32:33], v[34:35], v[38:39] op_sel:[1,0] op_sel_hi:[0,1]
	v_sub_f32_e32 v32, v32, v33
	v_mul_f32_e32 v37, 0x3e0293ee, v32
	v_pk_mul_f32 v[32:33], v[34:35], v[38:39]
	v_cvt_pk_bf16_f32 v155, v43, v37
	v_cvt_pk_bf16_f32 v148, v76, v74
	v_cvt_pk_bf16_f32 v149, v64, v66
	v_cvt_pk_bf16_f32 v150, v68, v62
	v_cvt_pk_bf16_f32 v151, v60, v58
	s_nop 0
	v_add_f32_e32 v32, v32, v33
	v_mul_f32_e32 v32, 0x3e0293ee, v32
	v_cvt_pk_bf16_f32 v144, v56, v54
	v_cvt_pk_bf16_f32 v145, v52, v50
	v_cvt_pk_bf16_f32 v146, v40, v42
	v_cvt_pk_bf16_f32 v147, v36, v32
	v_and_or_b32 v32, s8, 32, v178
	v_lshl_add_u32 v206, v176, 4, 16
	s_lshr_b32 s0, s97, 3
	s_and_b32 s0, s0, 0x1ffffff0
	v_mov_b32_e32 v33, s0
	v_mad_u32_u24 v32, v32, s82, v33
	v_lshl_or_b32 v32, v179, 3, v32
	v_lshlrev_b32_e32 v180, 1, v32
	s_lshr_b32 s0, s97, 4
	s_and_b32 s5, s0, 0xffffff0
	s_lshr_b32 s0, s97, 5
	v_and_or_b32 v32, s0, 2, v179
	s_lshr_b32 s18, s97, 4
	s_and_b32 s18, s18, 8
	v_bfe_u32 v33, v177, 2, 3
	v_or_b32_e32 v33, s5, v33
	v_or_b32_e32 v33, s18, v33
	v_lshlrev_b32_e32 v32, 5, v32
	v_mul_lo_u32 v33, v33, s82
	v_or3_b32 v32, v32, v204, v33
	v_lshlrev_b32_e32 v199, 1, v32
	v_add_u32_e32 v198, 0x80, v180
	v_add_u32_e32 v219, 0x48000, v199
	s_lshl_b32 s0, s33, 10
	s_add_i32 s74, s0, 16
	s_add_i32 s68, s0, 0x10010
	s_add_i32 m0, s74, 0
	s_nop 0
	global_load_lds_dwordx4 v180, s[72:73]
	s_add_i32 m0, s74, 8192
	s_nop 0
	global_load_lds_dwordx4 v198, s[72:73]
	s_add_u32 s72, s72, 0x90000
	s_addc_u32 s73, s73, 0
	s_add_i32 m0, s74, 16384
	s_nop 0
	global_load_lds_dwordx4 v180, s[72:73]
	s_add_i32 m0, s74, 24576
	s_nop 0
	global_load_lds_dwordx4 v198, s[72:73]
	s_add_u32 s72, s72, 0x90000
	s_addc_u32 s73, s73, 0
	s_add_i32 m0, s68, 0
	s_nop 0
	global_load_lds_dwordx4 v199, s[70:71]
	s_add_i32 m0, s68, 8192
	s_nop 0
	global_load_lds_dwordx4 v219, s[70:71]
	s_add_u32 s70, s70, 0x90000
	s_addc_u32 s71, s71, 0
	s_add_i32 m0, s74, 32768
	s_nop 0
	global_load_lds_dwordx4 v180, s[72:73]
	s_add_i32 m0, s74, 40960
	s_nop 0
	global_load_lds_dwordx4 v198, s[72:73]
	s_add_u32 s72, s72, 0x90000
	s_addc_u32 s73, s73, 0
	s_add_i32 m0, s68, 16384
	s_nop 0
	global_load_lds_dwordx4 v199, s[70:71]
	s_add_i32 m0, s68, 24576
	s_nop 0
	global_load_lds_dwordx4 v219, s[70:71]
	s_add_u32 s70, s70, 0x90000
	s_addc_u32 s71, s71, 0
	s_add_i32 m0, s74, 49152
	s_nop 0
	global_load_lds_dwordx4 v180, s[72:73]
	s_add_i32 m0, s74, 57344
	s_nop 0
	global_load_lds_dwordx4 v198, s[72:73]
	s_add_u32 s72, s72, 0x90000
	s_addc_u32 s73, s73, 0
	s_add_i32 m0, s68, 32768
	s_nop 0
	global_load_lds_dwordx4 v199, s[70:71]
	s_add_i32 m0, s68, 40960
	s_nop 0
	global_load_lds_dwordx4 v219, s[70:71]
	s_add_u32 s70, s70, 0x90000
	s_addc_u32 s71, s71, 0
	v_mov_b32_e32 v80, 0
	v_mov_b32_e32 v81, 0
	v_mov_b32_e32 v82, 0
	v_mov_b32_e32 v83, 0
	v_mov_b32_e32 v84, 0
	v_mov_b32_e32 v85, 0
	v_mov_b32_e32 v86, 0
	v_mov_b32_e32 v87, 0
	v_mov_b32_e32 v88, 0
	v_mov_b32_e32 v89, 0
	v_mov_b32_e32 v90, 0
	v_mov_b32_e32 v91, 0
	v_mov_b32_e32 v92, 0
	v_mov_b32_e32 v93, 0
	v_mov_b32_e32 v94, 0
	v_mov_b32_e32 v95, 0
	v_mov_b32_e32 v64, 0
	v_mov_b32_e32 v65, 0
	v_mov_b32_e32 v66, 0
	v_mov_b32_e32 v67, 0
	v_mov_b32_e32 v68, 0
	v_mov_b32_e32 v69, 0
	v_mov_b32_e32 v70, 0
	v_mov_b32_e32 v71, 0
	v_mov_b32_e32 v72, 0
	v_mov_b32_e32 v73, 0
	v_mov_b32_e32 v74, 0
	v_mov_b32_e32 v75, 0
	v_mov_b32_e32 v76, 0
	v_mov_b32_e32 v77, 0
	v_mov_b32_e32 v78, 0
	v_mov_b32_e32 v79, 0
	v_mov_b32_e32 v48, 0
	v_mov_b32_e32 v49, 0
	v_mov_b32_e32 v50, 0
	v_mov_b32_e32 v51, 0
	v_mov_b32_e32 v52, 0
	v_mov_b32_e32 v53, 0
	v_mov_b32_e32 v54, 0
	v_mov_b32_e32 v55, 0
	v_mov_b32_e32 v56, 0
	v_mov_b32_e32 v57, 0
	v_mov_b32_e32 v58, 0
	v_mov_b32_e32 v59, 0
	v_mov_b32_e32 v60, 0
	v_mov_b32_e32 v61, 0
	v_mov_b32_e32 v62, 0
	v_mov_b32_e32 v63, 0
	v_mov_b32_e32 v32, 0
	v_mov_b32_e32 v33, 0
	v_mov_b32_e32 v34, 0
	v_mov_b32_e32 v35, 0
	v_mov_b32_e32 v36, 0
	v_mov_b32_e32 v37, 0
	v_mov_b32_e32 v38, 0
	v_mov_b32_e32 v39, 0
	v_mov_b32_e32 v40, 0
	v_mov_b32_e32 v41, 0
	v_mov_b32_e32 v42, 0
	v_mov_b32_e32 v43, 0
	v_mov_b32_e32 v44, 0
	v_mov_b32_e32 v45, 0
	v_mov_b32_e32 v46, 0
	v_mov_b32_e32 v47, 0
	v_mov_b32_e32 v218, 0
	v_mov_b32_e32 v248, 0
	v_mov_b32_e32 v249, 0
	v_mov_b32_e32 v251, 0
	s_waitcnt vmcnt(4)
	s_barrier
	s_cmp_lt_u32 s33, 4
	s_cbranch_scc1 .Lattn_lead_in
	s_barrier
